# ssd pass1/pass3 head loops: top-of-head wait no longer covers the previous head's 4 stores (counted wait; full drain moved to the loop preheader)
# baseline (speedup 1.0000x reference)
.LBB0_957:
	s_or_b64 exec, exec, s[44:45]
	v_and_b32_e32 v1, 15, v40
	v_bfe_u32 v42, v40, 4, 2
	v_bfe_u32 v44, v40, 6, 2
	v_lshl_or_b32 v2, v44, 4, v1
	v_lshl_add_u32 v45, v42, 4, 0
	s_movk_i32 s44, 0x110
	v_mad_u32_u24 v86, v2, s44, v45
	v_ashrrev_i32_e32 v2, 2, v40
	v_and_b32_e32 v2, 0xffffffc0, v2
	s_lshl_b32 s38, s38, 10
	s_lshl_b32 s43, s47, 4
	v_or_b32_e32 v3, v2, v1
	v_or_b32_e32 v38, 16, v3
	s_or_b32 s38, s38, s43
	v_mul_lo_u32 v49, v38, s44
	v_or_b32_e32 v38, 32, v3
	s_or_b32 s38, s38, s33
	v_mul_lo_u32 v50, v38, s44
	v_add_lshl_u32 v38, s39, v41, 2
	s_ashr_i32 s39, s38, 31
	s_lshl_b64 s[38:39], s[38:39], 14
	s_add_u32 s33, s38, 0x19200040
	v_mul_lo_u32 v48, v3, s44
	v_or_b32_e32 v3, 48, v3
	s_addc_u32 s38, s39, 0
	v_mul_lo_u32 v51, v3, s44
	v_lshlrev_b32_e32 v1, 8, v1
	v_ashrrev_i32_e32 v3, 31, v2
	v_lshl_or_b32 v42, v42, 3, s33
	v_mov_b32_e32 v43, s38
	v_lshl_add_u64 v[2:3], v[2:3], 1, v[42:43]
	v_lshl_or_b32 v42, v44, 12, v1
	v_mov_b32_e32 v43, v0
	v_lshl_add_u32 v46, v36, 1, 0
	v_lshlrev_b32_e32 v87, 2, v36
	v_lshl_add_u64 v[78:79], v[2:3], 0, v[42:43]
	v_lshl_add_u64 v[2:3], s[40:41], 0, v[36:37]
	v_mov_b32_e32 v36, s42
	v_mov_b32_e32 v37, v0
	v_mul_u32_u24_e32 v47, 0x110, v41
	v_mov_b32_e32 v39, v0
	v_mad_u64_u32 v[36:37], s[38:39], v2, s84, v[36:37]
	v_and_b32_e32 v1, 7, v40
	v_lshl_add_u64 v[76:77], s[20:21], 0, v[38:39]
	v_mad_i32_i24 v81, v3, s84, v37
	v_lshl_or_b32 v80, v1, 4, v36
	v_lshl_add_u64 v[82:83], s[36:37], 0, v[38:39]
	s_mov_b64 s[38:39], 0
	v_add_u32_e32 v88, v46, v47
	v_add_u32_e32 v89, v45, v48
	v_add_u32_e32 v90, v45, v49
	v_add_u32_e32 v91, v45, v50
	v_add_u32_e32 v92, v45, v51
	v_readlane_b32 s33, v255, 19
	s_waitcnt vmcnt(0)
	s_branch .LBB0_960

.LBB0_960:
	v_lshl_add_u64 v[2:3], v[76:77], 0, s[38:39]
	v_lshl_add_u64 v[40:41], v[82:83], 0, s[38:39]
	v_mov_b32_e32 v1, s33
	ds_read_b32 v1, v1 offset:4604
	ds_read_b128 v[36:39], v222 offset:1152
	s_nop 0
	ds_read_b128 v[40:43], v222 offset:1024
	s_nop 0
	ds_read_b128 v[44:47], v222 offset:128
	ds_read_b128 v[48:51], v222
	s_waitcnt vmcnt(4)
	v_lshlrev_b32_e32 v52, 16, v8
	s_mov_b64 s[40:41], 0x1800
	v_and_b32_e32 v53, 0xffff0000, v8
	v_lshl_add_u64 v[56:57], v[2:3], 0, s[40:41]
	v_lshlrev_b32_e32 v54, 16, v9
	v_and_b32_e32 v55, 0xffff0000, v9
	v_lshlrev_b32_e32 v58, 16, v10
	v_and_b32_e32 v59, 0xffff0000, v10
	s_mov_b64 s[40:41], 0x3000
	v_lshl_add_u64 v[64:65], v[2:3], 0, s[40:41]
	s_mov_b64 s[40:41], 0x4800
	v_lshlrev_b32_e32 v60, 16, v11
	v_lshl_add_u64 v[72:73], v[2:3], 0, s[40:41]
	v_and_b32_e32 v61, 0xffff0000, v11
	s_movk_i32 s40, 0x3000
	v_lshlrev_b32_e32 v62, 16, v5
	v_and_b32_e32 v63, 0xffff0000, v5
	v_lshlrev_b32_e32 v66, 16, v6
	v_and_b32_e32 v67, 0xffff0000, v6
	v_lshlrev_b32_e32 v68, 16, v7
	v_and_b32_e32 v69, 0xffff0000, v7
	v_lshlrev_b32_e32 v70, 16, v13
	v_and_b32_e32 v71, 0xffff0000, v13
	v_lshlrev_b32_e32 v74, 16, v14
	v_and_b32_e32 v75, 0xffff0000, v14
	v_lshlrev_b32_e32 v84, 16, v15
	v_and_b32_e32 v85, 0xffff0000, v15
	v_lshlrev_b32_e32 v101, 16, v17
	v_and_b32_e32 v102, 0xffff0000, v17
	v_lshlrev_b32_e32 v103, 16, v18
	v_and_b32_e32 v104, 0xffff0000, v18
	v_lshlrev_b32_e32 v105, 16, v19
	v_and_b32_e32 v106, 0xffff0000, v19
	s_cmpk_eq_i32 s38, 0x700
	s_waitcnt lgkmcnt(0)
	v_fma_f32 v96, v44, v58, v36
	s_nop 0
	v_fma_f32 v100, v48, v52, v40
	v_add_co_u32_e32 v52, vcc, s69, v2
	v_fma_f32 v99, v49, v53, v41
	s_nop 0
	v_addc_co_u32_e32 v53, vcc, 0, v3, vcc
	v_fma_f32 v95, v45, v59, v37
	v_fma_f32 v98, v50, v54, v42
	v_fma_f32 v97, v51, v55, v43
	ds_read_b128 v[52:55], v222 offset:256
	s_nop 0
	ds_read_b128 v[56:59], v222 offset:384
	v_fma_f32 v94, v46, v60, v38
	v_lshlrev_b32_e32 v60, 16, v4
	v_fma_f32 v93, v47, v61, v39
	v_and_b32_e32 v61, 0xffff0000, v4
	s_waitcnt lgkmcnt(0)
	v_fmac_f32_e32 v100, v52, v60
	v_add_co_u32_e32 v60, vcc, s40, v2
	v_fmac_f32_e32 v99, v53, v61
	s_nop 0
	v_addc_co_u32_e32 v61, vcc, 0, v3, vcc
	s_nop 0
	v_fmac_f32_e32 v96, v56, v66
	v_fmac_f32_e32 v95, v57, v67
	v_fmac_f32_e32 v98, v54, v62
	v_fmac_f32_e32 v97, v55, v63
	ds_read_b128 v[60:63], v222 offset:512
	s_nop 0
	ds_read_b128 v[64:67], v222 offset:640
	s_movk_i32 s40, 0x4000
	v_add_co_u32_e32 v2, vcc, s40, v2
	v_fmac_f32_e32 v94, v58, v68
	v_fmac_f32_e32 v93, v59, v69
	v_lshlrev_b32_e32 v68, 16, v12
	v_and_b32_e32 v69, 0xffff0000, v12
	v_addc_co_u32_e32 v3, vcc, 0, v3, vcc
	s_waitcnt lgkmcnt(0)
	v_fmac_f32_e32 v100, v60, v68
	s_nop 0
	v_fmac_f32_e32 v96, v64, v74
	v_fmac_f32_e32 v99, v61, v69
	v_fmac_f32_e32 v95, v65, v75
	v_fmac_f32_e32 v98, v62, v70
	v_fmac_f32_e32 v97, v63, v71
	ds_read_b128 v[68:71], v222 offset:768
	s_nop 0
	ds_read_b128 v[72:75], v222 offset:896
	v_add_u32_e32 v222, 0x500, v222
	v_fmac_f32_e32 v94, v66, v84
	v_lshlrev_b32_e32 v84, 16, v16
	v_fmac_f32_e32 v93, v67, v85
	v_and_b32_e32 v85, 0xffff0000, v16
	s_waitcnt lgkmcnt(0)
	v_fmac_f32_e32 v100, v68, v84
	v_add_u32_e32 v84, s33, v87
	v_fmac_f32_e32 v99, v69, v85
	ds_read2st64_b32 v[2:3], v84 offset1:1
	ds_read2st64_b32 v[84:85], v84 offset0:16 offset1:17
	v_fmac_f32_e32 v98, v70, v101
	v_fmac_f32_e32 v97, v71, v102
	s_nop 0
	v_fmac_f32_e32 v96, v72, v103
	v_fmac_f32_e32 v95, v73, v104
	s_waitcnt lgkmcnt(0)
	v_sub_f32_e32 v84, v1, v84
	v_mul_f32_e32 v84, 0x3fb8aa3b, v84
	v_exp_f32_e32 v84, v84
	v_fmac_f32_e32 v94, v74, v105
	v_fmac_f32_e32 v93, v75, v106
	v_sub_f32_e32 v1, v1, v85
	v_mul_f32_e32 v2, v2, v84
	v_mul_f32_e32 v84, 0xbfb8aa3b, v100
	v_exp_f32_e32 v84, v84
	v_mul_f32_e32 v1, 0x3fb8aa3b, v1
	v_exp_f32_e32 v1, v1
	v_add_f32_e32 v84, 1.0, v84
	v_rcp_f32_e32 v84, v84
	v_mul_f32_e32 v1, v3, v1
	v_mul_f32_e32 v84, v100, v84
	v_mul_f32_e32 v84, v2, v84
	v_cvt_pk_bf16_f32 v84, v84, s0
	ds_write_b16 v88, v84 offset:34816
	v_mul_f32_e32 v84, 0xbfb8aa3b, v99
	v_exp_f32_e32 v84, v84
	s_nop 0
	v_add_f32_e32 v84, 1.0, v84
	v_rcp_f32_e32 v84, v84
	s_nop 0
	v_mul_f32_e32 v84, v99, v84
	v_mul_f32_e32 v84, v2, v84
	v_cvt_pk_bf16_f32 v84, v84, s0
	ds_write_b16 v88, v84 offset:35088
	v_mul_f32_e32 v84, 0xbfb8aa3b, v98
	v_exp_f32_e32 v84, v84
	s_nop 0
	v_add_f32_e32 v84, 1.0, v84
	v_rcp_f32_e32 v84, v84
	s_nop 0
	v_mul_f32_e32 v84, v98, v84
	v_mul_f32_e32 v84, v2, v84
	v_cvt_pk_bf16_f32 v84, v84, s0
	ds_write_b16 v88, v84 offset:35360
	v_mul_f32_e32 v84, 0xbfb8aa3b, v97
	v_exp_f32_e32 v84, v84
	v_and_b32_e32 v98, 0xffff0000, v23
	v_fmac_f32_e32 v39, v47, v98
	v_lshlrev_b32_e32 v47, 16, v26
	v_add_f32_e32 v84, 1.0, v84
	v_rcp_f32_e32 v84, v84
	s_nop 0
	v_mul_f32_e32 v84, v97, v84
	v_mul_f32_e32 v84, v2, v84
	v_cvt_pk_bf16_f32 v84, v84, s0
	ds_write_b16 v88, v84 offset:35632
	v_mul_f32_e32 v84, 0xbfb8aa3b, v96
	v_exp_f32_e32 v84, v84
	v_lshlrev_b32_e32 v97, 16, v23
	v_fma_f32 v38, v46, v97, v38
	v_and_b32_e32 v46, 0xffff0000, v25
	v_add_f32_e32 v84, 1.0, v84
	v_rcp_f32_e32 v84, v84
	s_nop 0
	v_mul_f32_e32 v84, v96, v84
	v_mul_f32_e32 v84, v2, v84
	v_cvt_pk_bf16_f32 v84, v84, s0
	ds_write_b16 v88, v84 offset:35904
	v_mul_f32_e32 v84, 0xbfb8aa3b, v95
	v_exp_f32_e32 v84, v84
	v_and_b32_e32 v96, 0xffff0000, v22
	v_fma_f32 v37, v45, v96, v37
	v_lshlrev_b32_e32 v45, 16, v25
	v_add_f32_e32 v84, 1.0, v84
	v_rcp_f32_e32 v84, v84
	s_nop 0
	v_mul_f32_e32 v84, v95, v84
	v_mul_f32_e32 v84, v2, v84
	v_cvt_pk_bf16_f32 v84, v84, s0
	ds_write_b16 v88, v84 offset:36176
	v_mul_f32_e32 v84, 0xbfb8aa3b, v94
	v_exp_f32_e32 v84, v84
	v_lshlrev_b32_e32 v95, 16, v22
	v_fma_f32 v36, v44, v95, v36
	v_and_b32_e32 v44, 0xffff0000, v24
	v_add_f32_e32 v84, 1.0, v84
	v_rcp_f32_e32 v84, v84
	v_fmac_f32_e32 v36, v56, v47
	v_lshlrev_b32_e32 v47, 16, v30
	v_fmac_f32_e32 v36, v64, v47
	v_mul_f32_e32 v84, v94, v84
	v_mul_f32_e32 v84, v2, v84
	v_cvt_pk_bf16_f32 v84, v84, s0
	ds_write_b16 v88, v84 offset:36448
	v_mul_f32_e32 v84, 0xbfb8aa3b, v93
	v_exp_f32_e32 v84, v84
	v_and_b32_e32 v94, 0xffff0000, v21
	v_fmac_f32_e32 v43, v51, v94
	v_fmac_f32_e32 v43, v55, v46
	v_add_f32_e32 v84, 1.0, v84
	v_rcp_f32_e32 v84, v84
	v_and_b32_e32 v46, 0xffff0000, v29
	v_fmac_f32_e32 v43, v63, v46
	v_and_b32_e32 v46, 0xffff0000, v33
	v_mul_f32_e32 v84, v93, v84
	v_mul_f32_e32 v2, v2, v84
	v_cvt_pk_bf16_f32 v2, v2, s0
	ds_write_b16 v88, v2 offset:36720
	v_lshlrev_b32_e32 v2, 16, v20
	v_and_b32_e32 v84, 0xffff0000, v20
	v_lshlrev_b32_e32 v93, 16, v21
	v_fma_f32 v2, v48, v2, v40
	v_fma_f32 v40, v49, v84, v41
	v_fma_f32 v41, v50, v93, v42
	v_lshlrev_b32_e32 v42, 16, v24
	v_fmac_f32_e32 v2, v52, v42
	v_lshlrev_b32_e32 v42, 16, v28
	v_fmac_f32_e32 v2, v60, v42
	v_lshlrev_b32_e32 v42, 16, v32
	v_fmac_f32_e32 v2, v68, v42
	v_mul_f32_e32 v3, 0xbfb8aa3b, v2
	v_exp_f32_e32 v3, v3
	v_fmac_f32_e32 v40, v53, v44
	v_and_b32_e32 v44, 0xffff0000, v28
	v_fmac_f32_e32 v40, v61, v44
	v_add_f32_e32 v3, 1.0, v3
	v_rcp_f32_e32 v3, v3
	v_and_b32_e32 v44, 0xffff0000, v32
	v_fmac_f32_e32 v40, v69, v44
	v_fmac_f32_e32 v41, v54, v45
	v_mul_f32_e32 v2, v2, v3
	v_mul_f32_e32 v2, v2, v1
	v_cvt_pk_bf16_f32 v2, v2, s0
	ds_write_b16 v88, v2 offset:34944
	v_mul_f32_e32 v2, 0xbfb8aa3b, v40
	v_exp_f32_e32 v2, v2
	v_lshlrev_b32_e32 v45, 16, v29
	v_fmac_f32_e32 v41, v62, v45
	v_lshlrev_b32_e32 v45, 16, v33
	v_add_f32_e32 v2, 1.0, v2
	v_rcp_f32_e32 v2, v2
	v_fmac_f32_e32 v41, v70, v45
	v_fmac_f32_e32 v43, v71, v46
	v_lshlrev_b32_e32 v47, 16, v34
	v_mul_f32_e32 v2, v40, v2
	v_mul_f32_e32 v2, v2, v1
	v_cvt_pk_bf16_f32 v2, v2, s0
	ds_write_b16 v88, v2 offset:35216
	v_mul_f32_e32 v2, 0xbfb8aa3b, v41
	v_exp_f32_e32 v2, v2
	v_fmac_f32_e32 v36, v72, v47
	v_and_b32_e32 v48, 0xffff0000, v26
	v_fmac_f32_e32 v37, v57, v48
	v_add_f32_e32 v2, 1.0, v2
	v_rcp_f32_e32 v2, v2
	v_and_b32_e32 v48, 0xffff0000, v30
	v_fmac_f32_e32 v37, v65, v48
	v_and_b32_e32 v48, 0xffff0000, v34
	v_mul_f32_e32 v2, v41, v2
	v_mul_f32_e32 v2, v2, v1
	v_cvt_pk_bf16_f32 v2, v2, s0
	ds_write_b16 v88, v2 offset:35488
	v_mul_f32_e32 v2, 0xbfb8aa3b, v43
	v_exp_f32_e32 v2, v2
	v_fmac_f32_e32 v37, v73, v48
	v_lshlrev_b32_e32 v49, 16, v27
	v_fmac_f32_e32 v38, v58, v49
	v_add_f32_e32 v2, 1.0, v2
	v_rcp_f32_e32 v2, v2
	v_lshlrev_b32_e32 v49, 16, v31
	v_fmac_f32_e32 v38, v66, v49
	v_lshlrev_b32_e32 v49, 16, v35
	v_mul_f32_e32 v2, v43, v2
	v_mul_f32_e32 v2, v2, v1
	v_cvt_pk_bf16_f32 v2, v2, s0
	ds_write_b16 v88, v2 offset:35760
	v_mul_f32_e32 v2, 0xbfb8aa3b, v36
	v_exp_f32_e32 v2, v2
	v_fmac_f32_e32 v38, v74, v49
	v_and_b32_e32 v50, 0xffff0000, v27
	v_fmac_f32_e32 v39, v59, v50
	v_add_f32_e32 v2, 1.0, v2
	v_rcp_f32_e32 v2, v2
	v_and_b32_e32 v50, 0xffff0000, v31
	v_fmac_f32_e32 v39, v67, v50
	v_and_b32_e32 v50, 0xffff0000, v35
	v_mul_f32_e32 v2, v36, v2
	v_mul_f32_e32 v2, v2, v1
	v_cvt_pk_bf16_f32 v2, v2, s0
	ds_write_b16 v88, v2 offset:36032
	v_mul_f32_e32 v2, 0xbfb8aa3b, v37
	v_exp_f32_e32 v2, v2
	v_fmac_f32_e32 v39, v75, v50
	v_add_f32_e32 v2, 1.0, v2
	v_rcp_f32_e32 v2, v2
	s_nop 0
	v_mul_f32_e32 v2, v37, v2
	v_mul_f32_e32 v2, v2, v1
	v_cvt_pk_bf16_f32 v2, v2, s0
	ds_write_b16 v88, v2 offset:36304
	v_mul_f32_e32 v2, 0xbfb8aa3b, v38
	v_exp_f32_e32 v2, v2
	s_nop 0
	v_add_f32_e32 v2, 1.0, v2
	v_rcp_f32_e32 v2, v2
	s_nop 0
	v_mul_f32_e32 v2, v38, v2
	v_mul_f32_e32 v2, v2, v1
	v_cvt_pk_bf16_f32 v2, v2, s0
	ds_write_b16 v88, v2 offset:36576
	v_mul_f32_e32 v2, 0xbfb8aa3b, v39
	v_exp_f32_e32 v2, v2
	s_nop 0
	v_add_f32_e32 v2, 1.0, v2
	v_rcp_f32_e32 v2, v2
	s_nop 0
	v_mul_f32_e32 v2, v39, v2
	v_mul_f32_e32 v1, v2, v1
	v_cvt_pk_bf16_f32 v1, v1, s0
	ds_write_b16 v88, v1 offset:36848
	s_waitcnt lgkmcnt(0)
	s_barrier
	s_cbranch_scc1 .LBB0_959
	v_mov_b32_e32 v6, v0
	v_mov_b32_e32 v7, v0
	v_mov_b32_e32 v4, v0
	v_mov_b32_e32 v5, v0
	v_mov_b64_e32 v[10:11], v[6:7]
	v_lshl_add_u64 v[36:37], s[2:3], 0, v[80:81]
	v_mov_b64_e32 v[8:9], v[4:5]
	s_and_saveexec_b64 s[40:41], s[4:5]
	s_cbranch_execz .LBB0_963
	v_add_co_u32_e32 v2, vcc, 0x31fa000, v36
	s_nop 1
	v_addc_co_u32_e32 v3, vcc, 0, v37, vcc
	global_load_dwordx4 v[8:11], v[2:3], off offset:3200

.LBB0_1123:
	s_or_b64 exec, exec, s[10:11]
	s_movk_i32 s5, 0x1100
	v_mul_lo_u32 v1, v87, s5
	v_readlane_b32 s5, v255, 22
	v_mul_u32_u24_e32 v194, 0x110, v88
	v_lshlrev_b32_e32 v154, 3, v151
	v_add_u32_e32 v1, s5, v1
	v_lshlrev_b32_e32 v84, 2, v151
	v_add3_u32 v195, v1, v194, v154
	v_or_b32_e32 v1, 3, v84
	v_cmp_gt_i32_e64 s[24:25], v1, v148
	v_or_b32_e32 v1, 17, v84
	v_cmp_gt_i32_e64 s[28:29], v1, v148
	v_or_b32_e32 v1, 19, v84
	v_cmp_gt_i32_e64 s[34:35], v1, v148
	v_or_b32_e32 v1, 33, v84
	v_cmp_gt_i32_e64 s[38:39], v1, v148
	v_or_b32_e32 v1, 35, v84
	v_or_b32_e32 v2, 2, v84
	v_cmp_gt_i32_e64 s[42:43], v1, v148
	v_or_b32_e32 v1, 49, v84
	v_cmp_gt_i32_e64 s[26:27], v2, v148
	v_or_b32_e32 v2, 18, v84
	v_cmp_gt_i32_e64 s[46:47], v1, v148
	v_or_b32_e32 v1, 51, v84
	v_writelane_b32 v255, s76, 52
	s_lshl_b32 s9, s4, 10
	s_lshl_b32 s10, s20, 4
	v_cmp_gt_i32_e64 s[36:37], v2, v148
	v_or_b32_e32 v2, 34, v84
	v_cmp_gt_i32_e64 s[50:51], v1, v148
	v_or_b32_e32 v1, 0x41, v84
	s_lshl_b32 s4, s76, 5
	v_readlane_b32 s76, v255, 33
	v_cmp_gt_i32_e64 s[44:45], v2, v148
	v_or_b32_e32 v2, 50, v84
	v_cmp_gt_i32_e64 s[54:55], v1, v148
	v_or_b32_e32 v1, 0x43, v84
	v_readlane_b32 s77, v255, 34
	s_add_u32 s4, s76, s4
	v_cmp_gt_i32_e64 s[52:53], v2, v148
	v_or_b32_e32 v2, 64, v84
	v_cmp_gt_i32_e64 s[58:59], v1, v148
	v_or_b32_e32 v1, 0x51, v84
	s_addc_u32 s5, s77, 0
	s_or_b32 s9, s9, s10
	v_cmp_gt_i32_e64 s[56:57], v2, v148
	v_or_b32_e32 v2, 0x42, v84
	v_cmp_gt_i32_e64 s[62:63], v1, v148
	v_or_b32_e32 v1, 0x53, v84
	s_or_b32 s10, s9, s13
	v_cmp_gt_i32_e64 s[60:61], v2, v148
	v_or_b32_e32 v2, 0x50, v84
	v_cmp_gt_i32_e64 s[66:67], v1, v148
	v_or_b32_e32 v1, 0x61, v84
	s_ashr_i32 s11, s10, 31
	v_cmp_gt_i32_e64 s[64:65], v2, v148
	v_or_b32_e32 v2, 0x52, v84
	v_cmp_gt_i32_e64 s[70:71], v1, v148
	v_or_b32_e32 v1, 0x63, v84
	s_lshl_b64 s[10:11], s[10:11], 14
	s_mov_b32 s9, s81
	v_cmp_gt_i32_e64 s[68:69], v2, v148
	v_or_b32_e32 v2, 0x60, v84
	v_cmp_gt_i32_e64 s[74:75], v1, v148
	v_lshlrev_b32_e32 v1, 8, v88
	v_and_b32_e32 v3, 48, v86
	s_add_u32 s6, s6, s12
	v_writelane_b32 v255, s8, 53
	v_ashrrev_i32_e32 v149, 31, v148
	v_cmp_gt_i32_e64 s[72:73], v2, v148
	v_or_b32_e32 v2, 0x62, v84
	v_or3_b32 v156, s10, v1, v3
	v_or_b32_e32 v1, 0x71, v84
	v_or_b32_e32 v85, 0x70, v84
	s_addc_u32 s7, s7, 0
	v_writelane_b32 v255, s9, 54
	s_mov_b32 s9, s81
	v_cmp_gt_i32_e64 s[20:21], v84, v148
	v_cmp_lt_i32_e64 s[22:23], v84, v148
	v_or_b32_e32 v94, 16, v84
	v_or_b32_e32 v95, 32, v84
	v_or_b32_e32 v92, 48, v84
	v_cmp_gt_i32_e64 s[76:77], v2, v148
	v_cmp_gt_i32_e64 s[78:79], v1, v148
	v_mov_b64_e32 v[2:3], s[8:9]
	v_cmp_gt_i32_e64 s[80:81], v85, v148
	v_or_b32_e32 v1, 0x73, v84
	v_or_b32_e32 v96, 0x72, v84
	v_lshl_add_u64 v[84:85], s[6:7], 0, v[148:149]
	v_mul_u32_u24_e32 v196, 0x110, v89
	v_lshl_add_u64 v[90:91], s[6:7], 0, v[152:153]
	v_cmp_gt_i32_e64 s[82:83], v1, v148
	v_lshlrev_b32_e32 v1, 2, v88
	v_add_lshl_u32 v158, s33, v89, 2
	v_mad_u64_u32 v[88:89], s[6:7], v84, s84, v[2:3]
	v_mad_i32_i24 v89, v85, s84, v89
	s_mov_b64 s[6:7], 0x3200800
	v_mul_u32_u24_e32 v197, 0x110, v92
	v_cmp_gt_i32_e64 s[48:49], v92, v148
	v_lshl_add_u64 v[84:85], v[88:89], 0, s[6:7]
	v_lshlrev_b32_e32 v92, 1, v92
	v_mov_b32_e32 v93, v0
	v_lshl_add_u64 v[160:161], v[84:85], 0, v[92:93]
	v_lshlrev_b32_e32 v92, 1, v95
	v_mov_b32_e32 v155, v0
	v_lshl_add_u64 v[162:163], v[84:85], 0, v[92:93]
	v_lshlrev_b32_e32 v92, 1, v94
	v_lshl_or_b32 v1, v87, 6, v1
	v_lshl_add_u64 v[164:165], v[84:85], 0, v[92:93]
	v_lshl_add_u64 v[84:85], v[88:89], 0, v[154:155]
	s_mov_b64 s[6:7], 0x3200840
	v_add_u32_e32 v200, s85, v1
	v_lshl_add_u64 v[166:167], v[84:85], 0, s[6:7]
	v_mad_u64_u32 v[2:3], s[6:7], v90, s84, v[2:3]
	v_and_b32_e32 v1, 7, v86
	v_readlane_b32 s8, v255, 39
	v_cmp_gt_i32_e64 s[30:31], v94, v148
	v_cmp_gt_i32_e64 s[40:41], v95, v148
	v_mov_b32_e32 v157, s11
	v_mul_u32_u24_e32 v153, 0x440, v151
	v_mul_u32_u24_e32 v198, 0x110, v94
	v_mul_u32_u24_e32 v199, 0x110, v95
	v_mov_b32_e32 v159, v0
	v_mad_i32_i24 v169, v91, s84, v3
	v_lshl_or_b32 v168, v1, 4, v2
	s_mov_b32 s33, 0
	s_mov_b32 s12, 0
	v_cmp_gt_i32_e64 s[84:85], v96, v148
	s_mov_b64 s[6:7], s[88:89]
	v_readlane_b32 s9, v255, 40
	s_waitcnt vmcnt(0)
	s_branch .LBB0_1126

.LBB0_1126:
	v_lshl_add_u64 v[2:3], s[6:7], 0, v[158:159]
	s_mov_b64 s[10:11], 0x1800
	v_lshl_add_u64 v[104:105], v[2:3], 0, s[10:11]
	s_movk_i32 s10, 0x1000
	v_add_co_u32_e32 v100, vcc, s10, v2
	s_mov_b64 s[10:11], 0x3000
	s_nop 0
	v_addc_co_u32_e32 v101, vcc, 0, v3, vcc
	v_lshl_add_u64 v[112:113], v[2:3], 0, s[10:11]
	s_movk_i32 s10, 0x3000
	v_lshl_add_u64 v[88:89], s[8:9], 0, v[158:159]
	v_add_co_u32_e32 v108, vcc, s10, v2
	s_mov_b64 s[10:11], 0x4800
	ds_read_b128 v[84:87], v222 offset:1152
	s_nop 0
	ds_read_b128 v[88:91], v222 offset:1024
	s_nop 0
	ds_read_b128 v[96:99], v222
	ds_read_b128 v[92:95], v222 offset:128
	v_addc_co_u32_e32 v109, vcc, 0, v3, vcc
	v_lshl_add_u64 v[116:117], v[2:3], 0, s[10:11]
	s_movk_i32 s10, 0x4000
	ds_read_b128 v[100:103], v222 offset:256
	s_nop 0
	ds_read_b128 v[104:107], v222 offset:384
	v_add_co_u32_e32 v2, vcc, s10, v2
	ds_read_b128 v[108:111], v222 offset:512
	s_nop 0
	ds_read_b128 v[112:115], v222 offset:640
	v_addc_co_u32_e32 v3, vcc, 0, v3, vcc
	ds_read_b128 v[120:123], v222 offset:768
	s_nop 0
	ds_read_b128 v[116:119], v222 offset:896
	v_add_u32_e32 v222, 0x500, v222
	v_lshl_add_u64 v[124:125], s[2:3], 0, v[156:157]
	s_mov_b32 s10, 0x19200000
	v_add_co_u32_e32 v2, vcc, s10, v124
	s_mov_b32 s10, 0x19201000
	s_nop 0
	v_addc_co_u32_e32 v3, vcc, 0, v125, vcc
	v_add_co_u32_e32 v130, vcc, s10, v124
	s_mov_b32 s10, 0x19202000
	s_nop 0
	v_addc_co_u32_e32 v131, vcc, 0, v125, vcc
	v_add_co_u32_e32 v128, vcc, s10, v124
	s_waitcnt vmcnt(4)
	v_lshlrev_b32_e32 v126, 16, v56
	v_addc_co_u32_e32 v129, vcc, 0, v125, vcc
	s_mov_b32 s10, 0x19203000
	v_lshlrev_b32_e32 v134, 16, v58
	v_lshlrev_b32_e32 v140, 16, v52
	v_add_co_u32_e32 v136, vcc, s10, v124
	v_and_b32_e32 v127, 0xffff0000, v56
	v_lshlrev_b32_e32 v144, 16, v54
	v_lshlrev_b32_e32 v155, 16, v60
	v_addc_co_u32_e32 v137, vcc, 0, v125, vcc
	v_and_b32_e32 v135, 0xffff0000, v58
	v_and_b32_e32 v139, 0xffff0000, v59
	v_and_b32_e32 v141, 0xffff0000, v52
	v_lshlrev_b32_e32 v173, 16, v62
	v_lshlrev_b32_e32 v177, 16, v64
	v_and_b32_e32 v145, 0xffff0000, v54
	v_and_b32_e32 v170, 0xffff0000, v60
	v_and_b32_e32 v174, 0xffff0000, v62
	v_and_b32_e32 v186, 0xffff0000, v64
	v_and_b32_e32 v133, 0xffff0000, v57
	v_and_b32_e32 v143, 0xffff0000, v53
	v_lshlrev_b32_e32 v138, 16, v59
	v_and_b32_e32 v172, 0xffff0000, v61
	s_bitcmp1_b32 s12, 0
	v_lshlrev_b32_e32 v132, 16, v57
	v_lshlrev_b32_e32 v142, 16, v53
	s_cselect_b32 s10, 0x4400, 0
	v_lshlrev_b32_e32 v171, 16, v61
	s_add_i32 s13, s10, 0
	v_lshlrev_b32_e32 v1, 1, v152
	v_lshlrev_b32_e32 v187, 16, v65
	s_add_i32 s13, s13, 0x11000
	v_add3_u32 v1, s13, v1, v196
	v_and_b32_e32 v147, 0xffff0000, v55
	v_and_b32_e32 v176, 0xffff0000, v63
	v_lshlrev_b32_e32 v146, 16, v55
	v_lshlrev_b32_e32 v175, 16, v63
	v_add_u32_e32 v206, s33, v150
	s_mov_b32 s10, 0x5040100
	s_cmpk_eq_i32 s33, 0xe00
	s_waitcnt lgkmcnt(0)
	v_fma_f32 v124, v96, v126, v88
	s_nop 0
	v_fma_f32 v125, v92, v134, v84
	v_fma_f32 v126, v97, v127, v89
	v_fma_f32 v127, v93, v135, v85
	v_fma_f32 v135, v95, v139, v87
	s_nop 0
	v_fmac_f32_e32 v124, v100, v140
	s_nop 0
	v_fmac_f32_e32 v125, v104, v144
	v_fmac_f32_e32 v126, v101, v141
	s_nop 0
	v_fmac_f32_e32 v124, v108, v155
	s_nop 0
	v_fmac_f32_e32 v125, v112, v173
	v_lshlrev_b32_e32 v139, 16, v66
	s_nop 0
	v_fmac_f32_e32 v124, v120, v177
	v_fmac_f32_e32 v127, v105, v145
	v_fmac_f32_e32 v126, v109, v170
	s_nop 0
	v_fmac_f32_e32 v125, v116, v139
	v_mul_f32_e32 v139, 0xbfb8aa3b, v124
	v_fmac_f32_e32 v127, v113, v174
	v_and_b32_e32 v140, 0xffff0000, v66
	v_fmac_f32_e32 v126, v121, v186
	v_exp_f32_e32 v139, v139
	v_fmac_f32_e32 v127, v117, v140
	v_mul_f32_e32 v140, 0xbfb8aa3b, v126
	v_exp_f32_e32 v140, v140
	v_fma_f32 v133, v99, v133, v91
	v_fmac_f32_e32 v133, v103, v143
	v_add_f32_e32 v139, 1.0, v139
	v_fma_f32 v134, v94, v138, v86
	v_fmac_f32_e32 v133, v111, v172
	v_and_b32_e32 v138, 0xffff0000, v65
	v_rcp_f32_e32 v139, v139
	v_fmac_f32_e32 v133, v123, v138
	v_add_f32_e32 v138, 1.0, v140
	v_fma_f32 v132, v98, v132, v90
	v_rcp_f32_e32 v138, v138
	v_fmac_f32_e32 v132, v102, v142
	v_fmac_f32_e32 v132, v110, v171
	v_mul_f32_e32 v124, v124, v139
	v_fmac_f32_e32 v132, v122, v187
	v_cvt_pk_bf16_f32 v124, v124, s0
	ds_write_b16 v1, v124
	v_mul_f32_e32 v124, v126, v138
	v_mul_f32_e32 v126, 0xbfb8aa3b, v132
	v_exp_f32_e32 v126, v126
	v_mul_f32_e32 v138, 0xbfb8aa3b, v133
	v_exp_f32_e32 v138, v138
	v_cvt_pk_bf16_f32 v124, v124, s0
	v_add_f32_e32 v126, 1.0, v126
	v_rcp_f32_e32 v126, v126
	ds_write_b16 v1, v124 offset:272
	v_add_f32_e32 v124, 1.0, v138
	v_rcp_f32_e32 v124, v124
	v_mul_f32_e32 v126, v132, v126
	v_cvt_pk_bf16_f32 v126, v126, s0
	ds_write_b16 v1, v126 offset:544
	v_mul_f32_e32 v126, 0xbfb8aa3b, v125
	v_exp_f32_e32 v126, v126
	v_mul_f32_e32 v132, 0xbfb8aa3b, v127
	v_exp_f32_e32 v132, v132
	v_mul_f32_e32 v124, v133, v124
	v_add_f32_e32 v126, 1.0, v126
	v_rcp_f32_e32 v126, v126
	v_fmac_f32_e32 v135, v107, v147
	v_cvt_pk_bf16_f32 v124, v124, s0
	v_fmac_f32_e32 v135, v115, v176
	v_and_b32_e32 v142, 0xffff0000, v67
	ds_write_b16 v1, v124 offset:816
	v_add_f32_e32 v124, 1.0, v132
	v_fmac_f32_e32 v134, v106, v146
	v_fmac_f32_e32 v135, v119, v142
	v_rcp_f32_e32 v124, v124
	v_fmac_f32_e32 v134, v114, v175
	v_lshlrev_b32_e32 v141, 16, v67
	v_mul_f32_e32 v125, v125, v126
	v_mul_f32_e32 v126, 0xbfb8aa3b, v135
	v_fmac_f32_e32 v134, v118, v141
	v_cvt_pk_bf16_f32 v125, v125, s0
	v_exp_f32_e32 v126, v126
	ds_write_b16 v1, v125 offset:1088
	v_mul_f32_e32 v125, 0xbfb8aa3b, v134
	v_mul_f32_e32 v124, v127, v124
	v_exp_f32_e32 v125, v125
	v_cvt_pk_bf16_f32 v124, v124, s0
	ds_write_b16 v1, v124 offset:1360
	v_add_f32_e32 v124, 1.0, v126
	v_rcp_f32_e32 v124, v124
	v_add_f32_e32 v125, 1.0, v125
	v_rcp_f32_e32 v125, v125
	v_lshlrev_b32_e32 v132, 16, v70
	v_mul_f32_e32 v124, v135, v124
	v_cvt_pk_bf16_f32 v124, v124, s0
	v_mul_f32_e32 v125, v134, v125
	ds_write_b16 v1, v124 offset:1904
	v_lshlrev_b32_e32 v124, 16, v68
	v_cvt_pk_bf16_f32 v125, v125, s0
	v_fma_f32 v88, v96, v124, v88
	v_fma_f32 v84, v92, v132, v84
	v_lshlrev_b32_e32 v92, 16, v72
	ds_write_b16 v1, v125 offset:1632
	v_and_b32_e32 v125, 0xffff0000, v68
	v_and_b32_e32 v133, 0xffff0000, v70
	v_fmac_f32_e32 v88, v100, v92
	v_lshlrev_b32_e32 v92, 16, v76
	v_fma_f32 v89, v97, v125, v89
	v_fma_f32 v85, v93, v133, v85
	v_and_b32_e32 v93, 0xffff0000, v72
	v_fmac_f32_e32 v88, v108, v92
	v_lshlrev_b32_e32 v92, 16, v80
	v_fmac_f32_e32 v89, v101, v93
	v_and_b32_e32 v93, 0xffff0000, v76
	v_fmac_f32_e32 v88, v120, v92
	v_fmac_f32_e32 v89, v109, v93
	v_and_b32_e32 v93, 0xffff0000, v80
	v_mul_f32_e32 v92, 0xbfb8aa3b, v88
	v_fmac_f32_e32 v89, v121, v93
	v_exp_f32_e32 v92, v92
	v_mul_f32_e32 v93, 0xbfb8aa3b, v89
	v_exp_f32_e32 v93, v93
	v_lshlrev_b32_e32 v126, 16, v69
	v_add_f32_e32 v92, 1.0, v92
	v_rcp_f32_e32 v92, v92
	v_lshlrev_b32_e32 v134, 16, v71
	v_add_f32_e32 v93, 1.0, v93
	v_fma_f32 v90, v98, v126, v90
	v_fma_f32 v86, v94, v134, v86
	v_lshlrev_b32_e32 v94, 16, v73
	v_rcp_f32_e32 v93, v93
	v_fmac_f32_e32 v90, v102, v94
	v_lshlrev_b32_e32 v94, 16, v77
	v_fmac_f32_e32 v90, v110, v94
	v_lshlrev_b32_e32 v94, 16, v81
	v_mul_f32_e32 v88, v88, v92
	v_fmac_f32_e32 v90, v122, v94
	v_cvt_pk_bf16_f32 v88, v88, s0
	ds_write_b16 v1, v88 offset:128
	v_mul_f32_e32 v88, v89, v93
	v_mul_f32_e32 v89, 0xbfb8aa3b, v90
	v_exp_f32_e32 v89, v89
	v_and_b32_e32 v127, 0xffff0000, v69
	v_and_b32_e32 v135, 0xffff0000, v71
	v_fmac_f32_e32 v91, v99, v127
	v_fmac_f32_e32 v87, v95, v135
	v_and_b32_e32 v95, 0xffff0000, v73
	v_fmac_f32_e32 v91, v103, v95
	v_and_b32_e32 v95, 0xffff0000, v77
	v_fmac_f32_e32 v91, v111, v95
	v_and_b32_e32 v95, 0xffff0000, v81
	v_add_f32_e32 v89, 1.0, v89
	v_fmac_f32_e32 v91, v123, v95
	v_rcp_f32_e32 v89, v89
	v_mul_f32_e32 v92, 0xbfb8aa3b, v91
	v_lshlrev_b32_e32 v96, 16, v74
	v_exp_f32_e32 v92, v92
	v_fmac_f32_e32 v84, v104, v96
	v_lshlrev_b32_e32 v96, 16, v78
	v_and_b32_e32 v97, 0xffff0000, v74
	v_fmac_f32_e32 v84, v112, v96
	v_lshlrev_b32_e32 v96, 16, v82
	v_mul_f32_e32 v89, v90, v89
	v_fmac_f32_e32 v85, v105, v97
	v_and_b32_e32 v97, 0xffff0000, v78
	v_fmac_f32_e32 v84, v116, v96
	v_cvt_pk_bf16_f32 v88, v88, s0
	v_cvt_pk_bf16_f32 v89, v89, s0
	v_fmac_f32_e32 v85, v113, v97
	v_and_b32_e32 v97, 0xffff0000, v82
	ds_write_b16 v1, v88 offset:400
	v_add_f32_e32 v88, 1.0, v92
	ds_write_b16 v1, v89 offset:672
	v_mul_f32_e32 v89, 0xbfb8aa3b, v84
	v_fmac_f32_e32 v85, v117, v97
	v_rcp_f32_e32 v88, v88
	v_exp_f32_e32 v89, v89
	v_mul_f32_e32 v90, 0xbfb8aa3b, v85
	v_exp_f32_e32 v90, v90
	v_mul_f32_e32 v88, v91, v88
	v_add_f32_e32 v89, 1.0, v89
	v_cvt_pk_bf16_f32 v88, v88, s0
	v_rcp_f32_e32 v89, v89
	ds_write_b16 v1, v88 offset:944
	v_add_f32_e32 v88, 1.0, v90
	v_lshlrev_b32_e32 v98, 16, v75
	v_and_b32_e32 v99, 0xffff0000, v75
	v_rcp_f32_e32 v88, v88
	v_fmac_f32_e32 v86, v106, v98
	v_fmac_f32_e32 v87, v107, v99
	v_lshlrev_b32_e32 v98, 16, v79
	v_and_b32_e32 v99, 0xffff0000, v79
	v_fmac_f32_e32 v86, v114, v98
	v_fmac_f32_e32 v87, v115, v99
	v_lshlrev_b32_e32 v98, 16, v83
	v_and_b32_e32 v99, 0xffff0000, v83
	v_mul_f32_e32 v84, v84, v89
	v_fmac_f32_e32 v86, v118, v98
	v_fmac_f32_e32 v87, v119, v99
	v_cvt_pk_bf16_f32 v84, v84, s0
	ds_write_b16 v1, v84 offset:1216
	v_mul_f32_e32 v84, v85, v88
	v_mul_f32_e32 v85, 0xbfb8aa3b, v86
	v_mul_f32_e32 v88, 0xbfb8aa3b, v87
	v_exp_f32_e32 v85, v85
	v_exp_f32_e32 v88, v88
	v_cvt_pk_bf16_f32 v84, v84, s0
	ds_write_b16 v1, v84 offset:1488
	v_add_f32_e32 v85, 1.0, v85
	v_add_f32_e32 v84, 1.0, v88
	v_rcp_f32_e32 v85, v85
	v_rcp_f32_e32 v84, v84
	v_lshl_add_u64 v[176:177], s[2:3], 0, v[166:167]
	v_mul_f32_e32 v85, v86, v85
	v_mul_f32_e32 v84, v87, v84
	v_cvt_pk_bf16_f32 v85, v85, s0
	v_cvt_pk_bf16_f32 v84, v84, s0
	ds_write_b16 v1, v85 offset:1760
	ds_write_b16 v1, v84 offset:2032
	v_add_u32_e32 v1, s33, v200
	v_add_u32_e32 v84, 0x23000, v206
	ds_read_b32 v155, v1
	ds_read_b128 v[84:87], v84
	v_add_u32_e32 v1, 0x22000, v206
	ds_read_b128 v[88:91], v1
	global_load_dwordx4 v[92:95], v[130:131], off offset:-4096
	global_load_dwordx4 v[100:103], v[130:131], off
	s_waitcnt lgkmcnt(1)
	v_sub_f32_e32 v1, v155, v84
	v_mul_f32_e32 v1, 0x3fb8aa3b, v1
	v_exp_f32_e32 v1, v1
	v_sub_f32_e32 v84, v155, v85
	v_mul_f32_e32 v84, 0x3fb8aa3b, v84
	v_sub_f32_e32 v85, v155, v87
	v_mul_f32_e32 v1, v20, v1
	s_waitcnt lgkmcnt(0)
	v_mul_f32_e32 v1, v88, v1
	v_exp_f32_e32 v88, v84
	v_sub_f32_e32 v84, v155, v86
	v_mul_f32_e32 v84, 0x3fb8aa3b, v84
	v_mul_f32_e32 v85, 0x3fb8aa3b, v85
	v_exp_f32_e32 v84, v84
	v_exp_f32_e32 v85, v85
	v_mul_f32_e32 v86, v21, v88
	v_mul_f32_e32 v86, v89, v86
	v_cndmask_b32_e64 v1, v1, 0, s[20:21]
	v_pk_mul_f32 v[84:85], v[22:23], v[84:85]
	v_cndmask_b32_e64 v86, 0, v86, s[22:23]
	v_pk_mul_f32 v[84:85], v[90:91], v[84:85]
	v_cvt_pk_bf16_f32 v86, v1, v86
	v_cvt_pk_bf16_f32 v1, v84, v85
	v_cndmask_b32_e64 v84, v1, 0, s[26:27]
	v_lshrrev_b32_e32 v1, 16, v1
	v_cndmask_b32_e64 v1, v1, 0, s[24:25]
	v_perm_b32 v87, v1, v84, s10
	ds_write_b64 v195, v[86:87]
	v_add_u32_e32 v1, 0x23040, v206
	ds_read_b128 v[84:87], v1
	v_add_u32_e32 v1, 0x22040, v206
	ds_read_b128 v[88:91], v1
	s_waitcnt lgkmcnt(1)
	v_sub_f32_e32 v1, v155, v84
	v_mul_f32_e32 v1, 0x3fb8aa3b, v1
	v_exp_f32_e32 v84, v1
	v_sub_f32_e32 v1, v155, v85
	v_mul_f32_e32 v1, 0x3fb8aa3b, v1
	v_exp_f32_e32 v85, v1
	v_sub_f32_e32 v1, v155, v86
	v_mul_f32_e32 v1, 0x3fb8aa3b, v1
	v_exp_f32_e32 v86, v1
	v_sub_f32_e32 v1, v155, v87
	v_mul_f32_e32 v1, 0x3fb8aa3b, v1
	v_exp_f32_e32 v87, v1
	v_pk_mul_f32 v[84:85], v[24:25], v[84:85]
	v_pk_mul_f32 v[86:87], v[26:27], v[86:87]
	s_waitcnt lgkmcnt(0)
	v_pk_mul_f32 v[84:85], v[88:89], v[84:85]
	v_pk_mul_f32 v[86:87], v[90:91], v[86:87]
	v_cvt_pk_bf16_f32 v1, v84, v85
	v_cndmask_b32_e64 v84, v1, 0, s[30:31]
	v_lshrrev_b32_e32 v1, 16, v1
	v_cndmask_b32_e64 v1, v1, 0, s[28:29]
	v_perm_b32 v84, v1, v84, s10
	v_cvt_pk_bf16_f32 v1, v86, v87
	v_cndmask_b32_e64 v85, v1, 0, s[36:37]
	v_lshrrev_b32_e32 v1, 16, v1
	v_cndmask_b32_e64 v1, v1, 0, s[34:35]
	v_perm_b32 v85, v1, v85, s10
	ds_write_b64 v195, v[84:85] offset:32
	v_add_u32_e32 v1, 0x23080, v206
	ds_read_b128 v[88:91], v1
	v_add_u32_e32 v1, 0x22080, v206
	global_load_dwordx4 v[112:115], v[136:137], off
	global_load_dwordx4 v[84:87], v[136:137], off offset:64
	ds_read_b128 v[96:99], v1
	s_waitcnt lgkmcnt(1)
	v_sub_f32_e32 v1, v155, v88
	v_mul_f32_e32 v1, 0x3fb8aa3b, v1
	v_exp_f32_e32 v104, v1
	v_sub_f32_e32 v1, v155, v89
	v_mul_f32_e32 v1, 0x3fb8aa3b, v1
	v_exp_f32_e32 v105, v1
	v_sub_f32_e32 v1, v155, v90
	v_mul_f32_e32 v1, 0x3fb8aa3b, v1
	v_exp_f32_e32 v106, v1
	v_sub_f32_e32 v1, v155, v91
	v_mul_f32_e32 v1, 0x3fb8aa3b, v1
	v_exp_f32_e32 v107, v1
	v_pk_mul_f32 v[104:105], v[28:29], v[104:105]
	global_load_dwordx4 v[108:111], v[2:3], off offset:64
	global_load_dwordx4 v[88:91], v[2:3], off offset:128
	s_waitcnt lgkmcnt(0)
	v_pk_mul_f32 v[96:97], v[96:97], v[104:105]
	v_pk_mul_f32 v[104:105], v[30:31], v[106:107]
	v_cvt_pk_bf16_f32 v1, v96, v97
	v_cndmask_b32_e64 v96, v1, 0, s[40:41]
	v_lshrrev_b32_e32 v1, 16, v1
	v_pk_mul_f32 v[98:99], v[98:99], v[104:105]
	v_cndmask_b32_e64 v1, v1, 0, s[38:39]
	v_perm_b32 v96, v1, v96, s10
	v_cvt_pk_bf16_f32 v1, v98, v99
	v_cndmask_b32_e64 v97, v1, 0, s[44:45]
	v_lshrrev_b32_e32 v1, 16, v1
	v_cndmask_b32_e64 v1, v1, 0, s[42:43]
	v_perm_b32 v97, v1, v97, s10
	ds_write_b64 v195, v[96:97] offset:64
	v_add_u32_e32 v1, 0x230c0, v206
	ds_read_b128 v[104:107], v1
	v_add_u32_e32 v1, 0x220c0, v206
	global_load_dwordx4 v[116:119], v[130:131], off offset:64
	global_load_dwordx4 v[96:99], v[130:131], off offset:128
	ds_read_b128 v[120:123], v1
	s_waitcnt lgkmcnt(1)
	v_sub_f32_e32 v1, v155, v104
	v_mul_f32_e32 v1, 0x3fb8aa3b, v1
	v_exp_f32_e32 v132, v1
	v_sub_f32_e32 v1, v155, v105
	v_mul_f32_e32 v1, 0x3fb8aa3b, v1
	v_exp_f32_e32 v133, v1
	v_sub_f32_e32 v1, v155, v106
	v_mul_f32_e32 v1, 0x3fb8aa3b, v1
	v_exp_f32_e32 v134, v1
	v_sub_f32_e32 v1, v155, v107
	v_mul_f32_e32 v1, 0x3fb8aa3b, v1
	v_exp_f32_e32 v135, v1
	global_load_dwordx4 v[124:127], v[128:129], off offset:64
	global_load_dwordx4 v[104:107], v[2:3], off offset:192
	v_pk_mul_f32 v[2:3], v[32:33], v[132:133]
	s_waitcnt lgkmcnt(0)
	v_pk_mul_f32 v[2:3], v[120:121], v[2:3]
	v_pk_mul_f32 v[120:121], v[34:35], v[134:135]
	v_cvt_pk_bf16_f32 v1, v2, v3
	v_cndmask_b32_e64 v2, v1, 0, s[48:49]
	v_lshrrev_b32_e32 v1, 16, v1
	v_pk_mul_f32 v[120:121], v[122:123], v[120:121]
	v_cndmask_b32_e64 v1, v1, 0, s[46:47]
	v_perm_b32 v2, v1, v2, s10
	v_cvt_pk_bf16_f32 v1, v120, v121
	v_cndmask_b32_e64 v3, v1, 0, s[52:53]
	v_lshrrev_b32_e32 v1, 16, v1
	v_cndmask_b32_e64 v1, v1, 0, s[50:51]
	v_perm_b32 v3, v1, v3, s10
	ds_write_b64 v195, v[2:3] offset:96
	v_add_u32_e32 v1, 0x23100, v206
	ds_read_b128 v[132:135], v1
	v_add_u32_e32 v1, 0x22100, v206
	global_load_dwordx4 v[144:147], v[136:137], off offset:-4096
	global_load_dwordx4 v[120:123], v[130:131], off offset:192
	ds_read_b128 v[138:141], v1
	s_waitcnt lgkmcnt(1)
	v_sub_f32_e32 v1, v155, v132
	v_mul_f32_e32 v1, 0x3fb8aa3b, v1
	v_exp_f32_e32 v2, v1
	v_sub_f32_e32 v1, v155, v133
	v_mul_f32_e32 v1, 0x3fb8aa3b, v1
	v_exp_f32_e32 v3, v1
	v_sub_f32_e32 v1, v155, v134
	v_mul_f32_e32 v1, 0x3fb8aa3b, v1
	v_exp_f32_e32 v142, v1
	v_sub_f32_e32 v1, v155, v135
	v_mul_f32_e32 v1, 0x3fb8aa3b, v1
	v_exp_f32_e32 v143, v1
	v_pk_mul_f32 v[2:3], v[36:37], v[2:3]
	global_load_dwordx4 v[132:135], v[128:129], off offset:128
	s_nop 0
	global_load_dwordx4 v[128:131], v[128:129], off offset:192
	s_waitcnt lgkmcnt(0)
	v_pk_mul_f32 v[2:3], v[138:139], v[2:3]
	v_pk_mul_f32 v[138:139], v[38:39], v[142:143]
	v_cvt_pk_bf16_f32 v1, v2, v3
	v_cndmask_b32_e64 v2, v1, 0, s[56:57]
	v_lshrrev_b32_e32 v1, 16, v1
	v_pk_mul_f32 v[138:139], v[140:141], v[138:139]
	v_cndmask_b32_e64 v1, v1, 0, s[54:55]
	v_perm_b32 v2, v1, v2, s10
	v_cvt_pk_bf16_f32 v1, v138, v139
	v_cndmask_b32_e64 v3, v1, 0, s[60:61]
	v_lshrrev_b32_e32 v1, 16, v1
	v_cndmask_b32_e64 v1, v1, 0, s[58:59]
	v_perm_b32 v3, v1, v3, s10
	ds_write_b64 v195, v[2:3] offset:128
	v_add_u32_e32 v1, 0x23140, v206
	ds_read_b128 v[170:173], v1
	v_add_u32_e32 v1, 0x22140, v206
	global_load_dwordx4 v[140:143], v[136:137], off offset:128
	s_nop 0
	global_load_dwordx4 v[136:139], v[136:137], off offset:192
	ds_read_b128 v[186:189], v1
	s_waitcnt lgkmcnt(1)
	v_sub_f32_e32 v1, v155, v170
	v_mul_f32_e32 v1, 0x3fb8aa3b, v1
	v_exp_f32_e32 v2, v1
	v_sub_f32_e32 v1, v155, v171
	v_mul_f32_e32 v1, 0x3fb8aa3b, v1
	v_exp_f32_e32 v3, v1
	v_sub_f32_e32 v1, v155, v172
	v_mul_f32_e32 v1, 0x3fb8aa3b, v1
	v_exp_f32_e32 v192, v1
	v_sub_f32_e32 v1, v155, v173
	global_load_dwordx2 v[190:191], v[176:177], off offset:-64
	global_load_dwordx2 v[174:175], v[176:177], off offset:-32
	global_load_dwordx2 v[172:173], v[176:177], off
	global_load_dwordx2 v[170:171], v[176:177], off offset:32
	v_mul_f32_e32 v1, 0x3fb8aa3b, v1
	v_exp_f32_e32 v193, v1
	v_pk_mul_f32 v[2:3], v[40:41], v[2:3]
	s_waitcnt lgkmcnt(0)
	v_pk_mul_f32 v[2:3], v[186:187], v[2:3]
	v_pk_mul_f32 v[186:187], v[42:43], v[192:193]
	v_cvt_pk_bf16_f32 v1, v2, v3
	v_cndmask_b32_e64 v2, v1, 0, s[64:65]
	v_lshrrev_b32_e32 v1, 16, v1
	v_pk_mul_f32 v[186:187], v[188:189], v[186:187]
	v_cndmask_b32_e64 v1, v1, 0, s[62:63]
	v_perm_b32 v2, v1, v2, s10
	v_cvt_pk_bf16_f32 v1, v186, v187
	v_cndmask_b32_e64 v3, v1, 0, s[68:69]
	v_lshrrev_b32_e32 v1, 16, v1
	v_cndmask_b32_e64 v1, v1, 0, s[66:67]
	v_perm_b32 v3, v1, v3, s10
	ds_write_b64 v195, v[2:3] offset:160
	v_add_u32_e32 v1, 0x23180, v206
	ds_read_b128 v[186:189], v1
	v_add_u32_e32 v1, 0x22180, v206
	ds_read_b128 v[202:205], v1
	s_waitcnt lgkmcnt(1)
	v_sub_f32_e32 v1, v155, v186
	v_mul_f32_e32 v1, 0x3fb8aa3b, v1
	v_exp_f32_e32 v2, v1
	v_sub_f32_e32 v1, v155, v187
	v_mul_f32_e32 v1, 0x3fb8aa3b, v1
	v_exp_f32_e32 v3, v1
	v_sub_f32_e32 v1, v155, v188
	v_mul_f32_e32 v1, 0x3fb8aa3b, v1
	v_exp_f32_e32 v186, v1
	v_sub_f32_e32 v1, v155, v189
	v_mul_f32_e32 v1, 0x3fb8aa3b, v1
	v_exp_f32_e32 v187, v1
	v_pk_mul_f32 v[2:3], v[44:45], v[2:3]
	v_pk_mul_f32 v[186:187], v[46:47], v[186:187]
	s_waitcnt lgkmcnt(0)
	v_pk_mul_f32 v[2:3], v[202:203], v[2:3]
	v_pk_mul_f32 v[186:187], v[204:205], v[186:187]
	v_cvt_pk_bf16_f32 v1, v2, v3
	v_cndmask_b32_e64 v2, v1, 0, s[72:73]
	v_lshrrev_b32_e32 v1, 16, v1
	v_cndmask_b32_e64 v1, v1, 0, s[70:71]
	v_perm_b32 v2, v1, v2, s10
	v_cvt_pk_bf16_f32 v1, v186, v187
	v_cndmask_b32_e64 v3, v1, 0, s[76:77]
	v_lshrrev_b32_e32 v1, 16, v1
	v_cndmask_b32_e64 v1, v1, 0, s[74:75]
	v_perm_b32 v3, v1, v3, s10
	ds_write_b64 v195, v[2:3] offset:192
	v_add_u32_e32 v1, 0x231c0, v206
	ds_read_b128 v[186:189], v1
	v_add_u32_e32 v1, 0x221c0, v206
	ds_read_b128 v[202:205], v1
	s_waitcnt lgkmcnt(1)
	v_sub_f32_e32 v1, v155, v186
	v_mul_f32_e32 v1, 0x3fb8aa3b, v1
	v_exp_f32_e32 v2, v1
	v_sub_f32_e32 v1, v155, v187
	v_mul_f32_e32 v1, 0x3fb8aa3b, v1
	v_exp_f32_e32 v3, v1
	v_sub_f32_e32 v1, v155, v188
	v_mul_f32_e32 v1, 0x3fb8aa3b, v1
	v_exp_f32_e32 v186, v1
	v_sub_f32_e32 v1, v155, v189
	v_mul_f32_e32 v1, 0x3fb8aa3b, v1
	v_exp_f32_e32 v187, v1
	v_pk_mul_f32 v[2:3], v[48:49], v[2:3]
	v_pk_mul_f32 v[186:187], v[50:51], v[186:187]
	s_waitcnt lgkmcnt(0)
	v_pk_mul_f32 v[2:3], v[202:203], v[2:3]
	v_pk_mul_f32 v[186:187], v[204:205], v[186:187]
	v_cvt_pk_bf16_f32 v1, v2, v3
	v_cndmask_b32_e64 v2, v1, 0, s[80:81]
	v_lshrrev_b32_e32 v1, 16, v1
	v_cndmask_b32_e64 v1, v1, 0, s[78:79]
	v_perm_b32 v2, v1, v2, s10
	v_cvt_pk_bf16_f32 v1, v186, v187
	v_cndmask_b32_e64 v3, v1, 0, s[84:85]
	v_lshrrev_b32_e32 v1, 16, v1
	v_cndmask_b32_e64 v1, v1, 0, s[82:83]
	v_perm_b32 v3, v1, v3, s10
	ds_write_b64 v195, v[2:3] offset:224
	s_waitcnt lgkmcnt(0)
	s_barrier
	s_cbranch_scc1 .LBB0_1125
	v_mov_b32_e32 v54, v0
	v_mov_b32_e32 v55, v0
	v_mov_b32_e32 v52, v0
	v_mov_b32_e32 v53, v0
	v_mov_b64_e32 v[58:59], v[54:55]
	v_lshl_add_u64 v[192:193], s[2:3], 0, v[168:169]
	v_mov_b64_e32 v[56:57], v[52:53]
	s_mov_b64 s[10:11], exec
	v_readlane_b32 vcc_lo, v255, 42
	v_readlane_b32 vcc_hi, v255, 43
	s_and_b64 vcc, s[10:11], vcc
	s_mov_b64 exec, vcc
	s_cbranch_execz .LBB0_1129
	v_add_co_u32_e32 v2, vcc, 0x31fa000, v192
	s_nop 1
	v_addc_co_u32_e32 v3, vcc, 0, v193, vcc
	global_load_dwordx4 v[56:59], v[2:3], off offset:3200
